# P2: half of each XCD's mixer workgroups (bx bit 3) run the prompt chunk summaries before the prompt attention units, the rest after
# baseline (speedup 1.0000x reference)
; #define LAS __attribute__((address_space(3)))
; __device__ __forceinline__ unsigned xb_add(unsigned* p, unsigned v) { return __hip_atomic_fetch_add(p, v, __ATOMIC_RELAXED, __HIP_MEMORY_SCOPE_AGENT); }
; __device__ __forceinline__ unsigned xb_xcc_id() { return (unsigned)__builtin_amdgcn_s_getreg((3 << 11) | 20) & 0xFu; }
; __device__ __forceinline__ XcdBarrier xcd_barrier_post(unsigned* bar, volatile LAS unsigned* st) {
;     XcdBarrier b; b.bar = bar; b.x = xb_xcc_id(); b.st = st;
;     if (threadIdx.x == 0) (void)xb_add(&bar[XB_XCNT(b.x)], 1u);
;     return b;
; __global__ void __launch_bounds__(512, 2) fwd_megakernel(Params P) {
;     ...
;     const int G = gridDim.x, bx = (int)blockIdx.x;
;     unsigned char* ws = P.ws;
;     volatile LAS unsigned* misc = (volatile LAS unsigned*)(lds + 131072 + 512);
;     const int wave0 = __builtin_amdgcn_readfirstlane((int)threadIdx.x >> 6);
;     if (threadIdx.x < 2) misc[threadIdx.x] = 0u;
;     __syncthreads();
;     XcdBarrier bar = xcd_barrier_post((unsigned*)(ws + WS_BAR), misc); bar.w0 = wave0;
_Z14fwd_megakernel6Params:
	s_mov_b32 s99, 0
	s_load_dwordx2 s[68:69], s[0:1], 0x70
	s_load_dwordx4 s[60:63], s[0:1], 0x60
	s_load_dwordx8 s[4:11], s[0:1], 0x40
	s_load_dword s96, s[0:1], 0x78
	v_readfirstlane_b32 s3, v0
	v_cmp_gt_u32_e32 vcc, 2, v0
	s_waitcnt lgkmcnt(0)
	v_writelane_b32 v255, s4, 0
	s_nop 1
	v_writelane_b32 v255, s5, 1
	v_writelane_b32 v255, s6, 2
	v_writelane_b32 v255, s7, 3
	v_writelane_b32 v255, s8, 4
	v_writelane_b32 v255, s9, 5
	v_writelane_b32 v255, s10, 6
	v_writelane_b32 v255, s11, 7
	s_add_u32 s4, s0, 0x78
	s_addc_u32 s5, s1, 0
	v_writelane_b32 v255, s4, 8
	s_nop 1
	v_writelane_b32 v255, s5, 9
	v_writelane_b32 v255, s3, 10
	s_and_saveexec_b64 s[4:5], vcc
	v_lshl_add_u32 v1, v0, 2, 0
	v_add_u32_e32 v1, 0x20200, v1
	v_mov_b32_e32 v2, 0
	ds_write_b32 v1, v2
	s_or_b64 exec, exec, s[4:5]
	s_add_u32 s4, s68, 0x80000
	s_addc_u32 s5, s69, 0
	s_waitcnt lgkmcnt(0)
	s_barrier
	v_writelane_b32 v255, s4, 11
	s_getreg_b32 s3, hwreg(HW_REG_XCC_ID, 0, 4)
	s_and_b32 s33, s3, 15
	v_writelane_b32 v255, s5, 12
	v_cmp_eq_u32_e32 vcc, 0, v0
	s_and_saveexec_b64 s[4:5], vcc
	s_cbranch_execz .LBB0_5
	s_mov_b64 s[6:7], exec
	v_mbcnt_lo_u32_b32 v0, s6, 0
	v_mbcnt_hi_u32_b32 v0, s7, v0
	v_cmp_eq_u32_e32 vcc, 0, v0
	s_and_b64 s[8:9], exec, vcc
	s_mov_b64 exec, s[8:9]
	s_cbranch_execz .LBB0_5
	s_bcnt1_i32_b64 s6, s[6:7]
	s_lshl_b32 s3, s33, 8
	v_mov_b32_e32 v1, s6
	v_readlane_b32 s6, v255, 11
	v_mov_b32_e32 v0, s3
	v_readlane_b32 s7, v255, 12
	s_nop 4
	global_atomic_add v0, v1, s[6:7] offset:1024
	s_and_b32 s98, s2, 7
	s_cmp_lg_u32 s98, s33
	s_cbranch_scc1 .Lxm_bad
	s_cmp_eq_u32 s96, 0x100
	s_cbranch_scc1 .Lxm_ok

; __global__ void __launch_bounds__(512, 2) fwd_megakernel(Params P) {
;     ...
;           const int vb = (GP % 8 == 0) ? (bx % 8) * (GP / 8) + bx / 8 : bx;
;           attn_prompt_loop(lds, P, GP, vb, tid, wave, lane);
;           retkv_loop(lds, P, 0, 1024, GP - 1 - vb, GP, tid, wave, lane);
.LBB0_568:
	s_cmp_lg_u32 s99, 0
	s_cbranch_scc1 .Lsw_goA
	s_bitcmp1_b32 s2, 3
	s_cbranch_scc0 .Lsw_goA
	s_mov_b32 s99, 1
	s_waitcnt vmcnt(0) lgkmcnt(0)
	s_barrier
	s_branch .LBB0_586

; DI void retkv_load(const bf16_t* Z, int ru, int tid, KvRegs& R) {
;     bool samp; int b, c, h, row0; ret_decode(ru, samp, b, c, h, row0);
; #pragma unroll
;     for (int i = 0; i < 2; ++i) { const int v = tid + 512 * i, j = v >> 4, d0 = (v & 15) * 8; const bf16_t* zr = Z + (size_t)(row0 + j) * INW;
;         R.k[i] = *(const u32x4*)(zr + 1280 + 128 * h + d0); R.v[i] = *(const u32x4*)(zr + 1792 + 128 * h + d0); }
; }
; DI void retkv_loop(lds_t* lds, const Params& P, int u_lo, int u_hi, int first, int G, int tid, int wave, int lane) {
;     const bf16_t* Z = (const bf16_t*)(P.ws + WS_Z);
;     KvRegs R; int u = u_lo + first;
;     if (u < u_hi) retkv_load(Z, u, tid, R);
;     for (; u < u_hi; u += G) {
;         bool samp; int b, c, h, row0; ret_decode(u, samp, b, c, h, row0);
.LBB0_586:
	s_cmp_eq_u32 s99, 2
	s_cbranch_scc1 .LBB0_591
	s_not_b32 s0, s3
	s_add_i32 s0, s77, s0
	s_cmpk_gt_i32 s0, 0x3ff
	s_cbranch_scc1 .LBB0_591
	s_lshl_b32 s1, s0, 4
	s_and_b32 s5, s1, 0xffffffc0
	v_ashrrev_i32_e32 v22, 4, v112
	s_waitcnt vmcnt(0)
	v_add_u32_e32 v0, s5, v22
	s_movk_i32 s4, 0x1600
	v_mov_b64_e32 v[8:9], s[74:75]
	s_lshl_b32 s0, s0, 8
	v_and_b32_e32 v18, 0x78, v114
	s_mov_b32 s1, 0
	s_waitcnt lgkmcnt(0)
	v_mad_i64_i32 v[0:1], s[6:7], v0, s4, v[8:9]
	s_and_b32 s0, s0, 0x300
	v_mov_b32_e32 v17, 0
	v_lshl_add_u64 v[0:1], v[0:1], 0, s[0:1]
	v_lshlrev_b32_e32 v16, 1, v18
	v_lshl_add_u64 v[10:11], v[0:1], 0, v[16:17]
	global_load_dwordx4 v[0:3], v[10:11], off offset:2560
	global_load_dwordx4 v[4:7], v[10:11], off offset:3584
	v_add_u32_e32 v10, 0x200, v112
	v_ashrrev_i32_e32 v23, 4, v10
	v_add_u32_e32 v10, s5, v23
	v_mad_i64_i32 v[8:9], s[6:7], v10, s4, v[8:9]
	v_lshl_add_u64 v[8:9], v[8:9], 0, s[0:1]
	v_lshl_add_u64 v[12:13], v[8:9], 0, v[16:17]
	global_load_dwordx4 v[8:11], v[12:13], off offset:2560
	s_nop 0
	global_load_dwordx4 v[12:15], v[12:13], off offset:3584
	v_bfe_u32 v20, v112, 2, 2
	v_lshrrev_b32_e32 v26, 1, v112
	s_movk_i32 s0, 0x110
	v_and_or_b32 v20, v26, 24, v20
	v_lshlrev_b32_e32 v26, 3, v113
	v_mul_lo_u32 v21, v22, s0
	v_mul_lo_u32 v30, v23, s0
	v_and_b32_e32 v26, 24, v26
	s_add_i32 s0, s65, 0
	v_lshlrev_b32_e32 v16, 4, v112
	v_add_u32_e32 v31, s0, v26
	v_readlane_b32 s0, v255, 13
	v_and_b32_e32 v16, 0xf0, v16
	s_lshl_b32 s0, s0, 4
	v_add_u32_e32 v19, 0, v16
	v_sub_u32_e32 v16, 63, v22
	s_add_u32 s5, s68, 0x9a00000
	v_cvt_f32_i32_e32 v24, v16
	v_sub_u32_e32 v16, 63, v23
	s_addc_u32 s6, s69, 0
	s_lshl_b32 s9, s96, 1
	v_cvt_f32_i32_e32 v25, v16
	s_add_i32 s12, s9, -1
	v_lshrrev_b32_e32 v16, 2, v112
	v_mul_u32_u24_e32 v33, 0x110, v20
	v_lshlrev_b32_e32 v20, 7, v112
	s_sub_i32 s8, 0, s3
	s_sub_i32 s3, s12, s3
	s_lshl_b32 s13, s49, 1
	s_lshl_b32 s9, s96, 4
	s_lshl_b32 s11, s49, 4
	v_add_u32_e32 v32, 0, v26
	v_and_b32_e32 v20, 0x780, v20
	v_and_b32_e32 v16, 12, v16
	s_not_b32 s7, s49
	s_sub_i32 s10, s3, s13
	s_sub_i32 s9, s9, s11
	s_lshl_b32 s11, s96, 7
	s_lshl_b32 s14, s49, 7
	s_add_i32 s7, s7, s96
	s_lshl_b32 s3, s10, 4
	s_lshl_b32 s10, s10, 7
	s_sub_i32 s11, s11, s14
	s_sub_i32 s12, s12, s13
	s_mov_b32 s13, 0xc2fc0000
	v_mov_b32_e32 v26, 0x42800000
	s_mov_b32 s14, 0x800000
	v_mov_b32_e32 v27, 0x42000000
	v_not_b32_e32 v28, 63
	v_add_u32_e32 v29, v19, v21
	v_add_u32_e32 v30, v19, v30
	v_lshlrev_b32_e32 v18, 1, v18
	v_add_u32_e32 v31, v31, v33
	v_add_u32_e32 v32, v32, v33
	s_lshl_b32 s15, s0, 1
	v_lshlrev_b32_e32 v16, 1, v16
	v_lshlrev_b32_e32 v20, 1, v20
	s_movk_i32 s16, 0x2000
	s_movk_i32 s17, 0x4000
	s_movk_i32 s18, 0x6000
	s_branch .LBB0_589

; __global__ void __launch_bounds__(512, 2) fwd_megakernel(Params P) {
;     ...
;           const int vb = (GP % 8 == 0) ? (bx % 8) * (GP / 8) + bx / 8 : bx;
;           attn_prompt_loop(lds, P, GP, vb, tid, wave, lane);
;           retkv_loop(lds, P, 0, 1024, GP - 1 - vb, GP, tid, wave, lane);
;         }
.LBB0_591:
	s_cmp_lg_u32 s99, 1
	s_cbranch_scc1 .Lsw_done
	s_mov_b32 s99, 2
	s_waitcnt vmcnt(0) lgkmcnt(0)
	s_barrier
	s_branch .LBB0_565
